# NSA selected loop: back-edge rotation - exit test, next V addresses and selection-mask computation moved in front of the step barrier so the segment starts with DMA issue and K reads
# speedup vs baseline: 1.0065x; 1.0065x over previous
; template <bool FX>
; DI void nsa_tile(const Params& p, int b, int g, int tile, bf16_t* lds, const float CL) {
;     ...
;       for (int s = 0; s <= cur; ++s) {
;         __syncthreads();
;         tile64_sstore(tid, Ks, rk0, rk1);
;         tile64_sstore(tid, Vs, rv0, rv1);
;         __syncthreads();
;         if (s < cur) {
;           tile64_gload(tid, rk0, rk1, kb + (size_t)(s + 1) * 64 * ZS, ZS);
;           tile64_gload(tid, rv0, rv1, vsT + (s + 1) * 64, TS);
;         }
;         uint32_t wsel = (s < 32) ? sw0 : (s < 64) ? sw1 : (s < 96) ? sw2 : sw3;
;         bool sel = (wsel >> (s & 31)) & 1u;
;         int hi = sel ? (tok - s * 64) : -1;
;         if (__any(hi >= 0)) attn_compute<2, FX>(lane, Ks, Vs, qf, st, invl, 0, hi, dA, dE, CL);
.LBB0_668:
	s_add_i32 s68, s68, 1
	s_lshl_b64 s[2:3], s[28:29], 1
	s_add_u32 s2, s12, s2
	s_addc_u32 s3, s13, s3
	v_lshl_add_u64 v[66:67], v[138:139], 1, s[2:3]
	v_lshl_add_u64 v[68:69], v[142:143], 1, s[2:3]
	v_lshl_add_u64 v[66:67], v[66:67], 0, v[202:203]
	v_lshl_add_u64 v[70:71], v[68:69], 0, v[202:203]
	s_cmp_lt_u32 s68, 32
	s_cselect_b64 vcc, -1, 0
	s_cmp_lt_u32 s68, 64
	s_cselect_b64 s[2:3], -1, 0
	s_cmpk_lt_u32 s68, 0x60
	s_cselect_b64 s[4:5], -1, 0
	v_cndmask_b32_e64 v74, v183, v182, s[4:5]
	v_cndmask_b32_e64 v74, v74, v181, s[2:3]
	v_cndmask_b32_e32 v74, v74, v180, vcc
	v_lshrrev_b32_e32 v74, s68, v74
	v_and_b32_e32 v74, 1, v74
	v_cmp_eq_u32_e32 vcc, 1, v74
	s_nop 1
	v_cndmask_b32_e32 v215, -1, v187, vcc
	v_cmp_lt_i32_e32 vcc, -1, v215
	s_cmp_ge_u32 s68, s25
	s_waitcnt vmcnt(0)
	s_barrier
	s_cbranch_scc1 .LBB0_670
	s_mov_b32 m0, s76
	s_nop 0
	global_load_lds_dwordx4 v[158:159], off
	s_add_u32 m0, s76, 0x1000
	s_nop 0
	global_load_lds_dwordx4 v[160:161], off
	s_add_u32 m0, s76, 0x2000
	s_nop 0
	global_load_lds_dwordx4 v[66:67], off
	s_add_u32 m0, s76, 0x3000
	s_nop 0
	global_load_lds_dwordx4 v[70:71], off
	s_xor_b32 s76, s76, 0xc000
; DI f32x4 mfma16(bf16x8 a, bf16x8 b, f32x4 c) { return __builtin_amdgcn_mfma_f32_16x16x32_bf16(a, b, c, 0, 0, 0); }
; template <int MODE, bool FX>
; DI void attn_compute(const int lane, const bf16_t* Ks, const bf16_t* Vs, const bf16x8 (&qf)[2][2], AttnSt& st, const float (&invl)[2],
;                      int lo, int hi, float (&impA)[4], float (&impE)[4], const float CL) {
;     ...
;   for (int ks = 0; ks < 2; ++ks) {
; #pragma unroll
;     for (int kt = 0; kt < 4; ++kt) {
;       int row = kt * 16 + col;
;       bf16x8 kf = *(const bf16x8*)(Ks + row * 64 + (((ks * 4 + quad) ^ ((row >> 1) & 7)) << 3));
; #pragma unroll
;       for (int hh = 0; hh < 2; ++hh) S[kt][hh] = mfma16(kf, qf[hh][ks], S[kt][hh]);
;     }
;   }
;   bf16x8 pf[2][2];
;   const bool full = (lo <= 0) && (hi >= 63);
;   const bool none = (hi < 0) || (lo > 63) || (hi < lo);
;   if (__all(full || none)) {
;     ...
;     if (FX) {
;       constexpr float L2E = 1.4426950408889634f;
;       const float il = (MODE == 1) ? invl[hh] : 1.f;
;       float rs = 0.f;
; #pragma unroll
;       for (int kt = 0; kt < 4; ++kt) {
;         float a = 0.f;
; #pragma unroll
;         for (int j = 0; j < 4; ++j) {
;           const int kl = kt * 16 + quad * 4 + j;
;           const bool v = (kl >= lo) && (kl <= hi);
;           float pv = v ? __builtin_amdgcn_exp2f(fmaf(S[kt][hh][j], L2E, -CL)) : 0.f;
;           if (MODE == 1) pv *= il;
;           S[kt][hh][j] = pv;
;           a += pv;
;         }
;         rs += a;
;         if (MODE == 1) {
;           impA[kt] += a;
;           impE[kt] += S[kt][hh][3];
;         }
;       }
;       if (MODE != 1 && !(FX && MODE == 2)) st.l[hh] += rs;
;       if (MODE != 0) {
; #pragma unroll
;         for (int c = 0; c < 2; ++c)
;           pf[hh][c] = mk8(pack2(S[2 * c][hh][0], S[2 * c][hh][1]), pack2(S[2 * c][hh][2], S[2 * c][hh][3]),
;                           pack2(S[2 * c + 1][hh][0], S[2 * c + 1][hh][1]), pack2(S[2 * c + 1][hh][2], S[2 * c + 1][hh][3]));
;       }
.LBB0_670:
	s_cbranch_vccz .LBB0_667
	ds_read_b128 v[220:223], v188
	ds_read_b128 v[224:227], v188 offset:2048
	ds_read_b128 v[228:231], v188 offset:4096
	ds_read_b128 v[232:235], v189
	ds_read_b128 v[236:239], v190
	ds_read_b128 v[240:243], v190 offset:2048
	ds_read_b128 v[244:247], v190 offset:4096
	ds_read_b128 v[198:201], v191
	v_cmp_lt_u32_e32 vcc, 62, v215
	s_mov_b64 s[2:3], -1
	s_cmp_eq_u64 vcc, exec
	s_cbranch_scc1 .Lnsa_fast
	s_waitcnt lgkmcnt(7)
	v_mfma_f32_16x16x32_bf16 v[98:101], v[220:223], v[2:5], 0
	v_mfma_f32_16x16x32_bf16 v[90:93], v[220:223], v[10:13], 0
	s_waitcnt lgkmcnt(6)
	v_mfma_f32_16x16x32_bf16 v[106:109], v[224:227], v[2:5], 0
	v_mfma_f32_16x16x32_bf16 v[94:97], v[224:227], v[10:13], 0
	s_waitcnt lgkmcnt(5)
	v_mfma_f32_16x16x32_bf16 v[102:105], v[228:231], v[2:5], 0
	v_mfma_f32_16x16x32_bf16 v[82:85], v[228:231], v[10:13], 0
	s_waitcnt lgkmcnt(4)
	v_mfma_f32_16x16x32_bf16 v[110:113], v[232:235], v[2:5], 0
	v_mfma_f32_16x16x32_bf16 v[86:89], v[232:235], v[10:13], 0
	s_waitcnt lgkmcnt(3)
	v_mfma_f32_16x16x32_bf16 v[98:101], v[236:239], v[6:9], v[98:101]
	v_mfma_f32_16x16x32_bf16 v[90:93], v[236:239], v[14:17], v[90:93]
	s_waitcnt lgkmcnt(2)
	v_mfma_f32_16x16x32_bf16 v[106:109], v[240:243], v[6:9], v[106:109]
	v_mfma_f32_16x16x32_bf16 v[94:97], v[240:243], v[14:17], v[94:97]
	s_waitcnt lgkmcnt(1)
	v_mfma_f32_16x16x32_bf16 v[102:105], v[244:247], v[6:9], v[102:105]
	v_mfma_f32_16x16x32_bf16 v[82:85], v[244:247], v[14:17], v[82:85]
	s_waitcnt lgkmcnt(0)
	v_mfma_f32_16x16x32_bf16 v[110:113], v[198:201], v[6:9], v[110:113]
	v_mfma_f32_16x16x32_bf16 v[86:89], v[198:201], v[14:17], v[86:89]
	ds_read_b64 v[220:221], v207 offset:8192
	ds_read_b64 v[222:223], v208 offset:8192
	ds_read_b64 v[224:225], v209 offset:8192
	ds_read_b64 v[226:227], v210 offset:8192
	ds_read_b64 v[228:229], v207 offset:10240
	ds_read_b64 v[230:231], v208 offset:10240
	ds_read_b64 v[232:233], v209 offset:10240
	ds_read_b64 v[234:235], v210 offset:10240
	ds_read_b64 v[236:237], v207 offset:12288
	ds_read_b64 v[238:239], v208 offset:12288
	ds_read_b64 v[240:241], v209 offset:12288
	ds_read_b64 v[242:243], v210 offset:12288
	ds_read_b64 v[244:245], v211 offset:8192
	ds_read_b64 v[246:247], v212 offset:8192
	ds_read_b64 v[198:199], v213 offset:8192
	ds_read_b64 v[200:201], v214 offset:8192
	s_cbranch_scc1 .LBB0_673
	v_fmamk_f32 v74, v98, 0x3fb8aa3b, v205
	v_fmamk_f32 v75, v99, 0x3fb8aa3b, v205
	v_fmamk_f32 v76, v100, 0x3fb8aa3b, v205
	v_fmamk_f32 v77, v101, 0x3fb8aa3b, v205
	v_fmamk_f32 v78, v106, 0x3fb8aa3b, v205
	v_fmamk_f32 v79, v107, 0x3fb8aa3b, v205
	v_fmamk_f32 v80, v108, 0x3fb8aa3b, v205
	v_fmamk_f32 v81, v109, 0x3fb8aa3b, v205
	v_fmamk_f32 v164, v102, 0x3fb8aa3b, v205
	v_fmamk_f32 v165, v103, 0x3fb8aa3b, v205
	v_fmamk_f32 v166, v104, 0x3fb8aa3b, v205
	v_fmamk_f32 v167, v105, 0x3fb8aa3b, v205
	v_fmamk_f32 v168, v110, 0x3fb8aa3b, v205
	v_fmamk_f32 v169, v111, 0x3fb8aa3b, v205
	v_fmamk_f32 v170, v112, 0x3fb8aa3b, v205
	v_fmamk_f32 v171, v113, 0x3fb8aa3b, v205
	v_exp_f32_e32 v74, v74
	v_exp_f32_e32 v75, v75
	v_exp_f32_e32 v76, v76
	v_exp_f32_e32 v77, v77
	v_exp_f32_e32 v78, v78
	v_exp_f32_e32 v79, v79
	v_exp_f32_e32 v80, v80
	v_exp_f32_e32 v81, v81
	v_exp_f32_e32 v164, v164
	v_exp_f32_e32 v165, v165
	v_exp_f32_e32 v166, v166
	v_exp_f32_e32 v167, v167
	v_exp_f32_e32 v168, v168
	v_exp_f32_e32 v169, v169
	v_exp_f32_e32 v170, v170
	v_exp_f32_e32 v171, v171
	v_cmp_gt_i32_e32 vcc, v118, v215
	v_cmp_lt_i32_e64 s[2:3], v118, v215
	v_cmp_gt_i32_e64 s[52:53], v119, v215
	v_cmp_gt_i32_e64 s[54:55], v192, v215
	v_cmp_gt_i32_e64 s[40:41], v120, v215
	v_cmp_gt_i32_e64 s[42:43], v193, v215
	v_cmp_gt_i32_e64 s[56:57], v122, v215
	v_cmp_gt_i32_e64 s[58:59], v121, v215
	v_cmp_gt_i32_e64 s[44:45], v194, v215
	v_cmp_gt_i32_e64 s[46:47], v195, v215
	v_cmp_gt_i32_e64 s[60:61], v206, v215
	v_cmp_gt_i32_e64 s[62:63], v124, v215
	v_cmp_gt_i32_e64 s[48:49], v126, v215
	v_cmp_gt_i32_e64 s[50:51], v123, v215
	v_cmp_gt_i32_e64 s[64:65], v125, v215
	v_cmp_gt_i32_e64 s[66:67], v127, v215
	v_cndmask_b32_e64 v74, v74, 0, vcc
	v_cndmask_b32_e64 v75, 0, v75, s[2:3]
	v_cndmask_b32_e64 v76, v76, 0, s[52:53]
	v_cndmask_b32_e64 v77, v77, 0, s[54:55]
	v_cndmask_b32_e64 v78, v78, 0, s[40:41]
	v_cndmask_b32_e64 v79, v79, 0, s[42:43]
	v_cndmask_b32_e64 v80, v80, 0, s[56:57]
	v_cndmask_b32_e64 v81, v81, 0, s[58:59]
	v_cndmask_b32_e64 v164, v164, 0, s[44:45]
	v_cndmask_b32_e64 v165, v165, 0, s[46:47]
	v_cndmask_b32_e64 v166, v166, 0, s[60:61]
	v_cndmask_b32_e64 v167, v167, 0, s[62:63]
	v_cndmask_b32_e64 v168, v168, 0, s[48:49]
	v_cndmask_b32_e64 v169, v169, 0, s[50:51]
	v_cndmask_b32_e64 v170, v170, 0, s[64:65]
	v_cndmask_b32_e64 v171, v171, 0, s[66:67]
	v_cvt_pk_bf16_f32 v74, v74, v75
	v_cvt_pk_bf16_f32 v75, v76, v77
	v_cvt_pk_bf16_f32 v76, v78, v79
	v_cvt_pk_bf16_f32 v77, v80, v81
	v_cvt_pk_bf16_f32 v78, v164, v165
	v_cvt_pk_bf16_f32 v79, v166, v167
	v_cvt_pk_bf16_f32 v80, v168, v169
	v_cvt_pk_bf16_f32 v81, v170, v171
	v_fmamk_f32 v164, v90, 0x3fb8aa3b, v205
	v_fmamk_f32 v165, v91, 0x3fb8aa3b, v205
	v_fmamk_f32 v166, v92, 0x3fb8aa3b, v205
	v_fmamk_f32 v167, v93, 0x3fb8aa3b, v205
	v_fmamk_f32 v168, v94, 0x3fb8aa3b, v205
	v_fmamk_f32 v169, v95, 0x3fb8aa3b, v205
	v_fmamk_f32 v170, v96, 0x3fb8aa3b, v205
	v_fmamk_f32 v171, v97, 0x3fb8aa3b, v205
	v_fmamk_f32 v172, v82, 0x3fb8aa3b, v205
	v_fmamk_f32 v173, v83, 0x3fb8aa3b, v205
	v_fmamk_f32 v174, v84, 0x3fb8aa3b, v205
	v_fmamk_f32 v175, v85, 0x3fb8aa3b, v205
	v_fmamk_f32 v176, v86, 0x3fb8aa3b, v205
	v_fmamk_f32 v177, v87, 0x3fb8aa3b, v205
	v_fmamk_f32 v178, v88, 0x3fb8aa3b, v205
	v_fmamk_f32 v179, v89, 0x3fb8aa3b, v205
	v_exp_f32_e32 v164, v164
	v_exp_f32_e32 v165, v165
	v_exp_f32_e32 v166, v166
	v_exp_f32_e32 v167, v167
	v_exp_f32_e32 v168, v168
	v_exp_f32_e32 v169, v169
	v_exp_f32_e32 v170, v170
	v_exp_f32_e32 v171, v171
	v_exp_f32_e32 v172, v172
	v_exp_f32_e32 v173, v173
	v_exp_f32_e32 v174, v174
	v_exp_f32_e32 v175, v175
	v_exp_f32_e32 v176, v176
	v_exp_f32_e32 v177, v177
	v_exp_f32_e32 v178, v178
	v_exp_f32_e32 v179, v179
	v_cndmask_b32_e64 v164, v164, 0, vcc
	v_cndmask_b32_e64 v165, 0, v165, s[2:3]
	v_cndmask_b32_e64 v166, v166, 0, s[52:53]
	v_cndmask_b32_e64 v167, v167, 0, s[54:55]
	v_cndmask_b32_e64 v168, v168, 0, s[40:41]
	v_cndmask_b32_e64 v169, v169, 0, s[42:43]
	v_cndmask_b32_e64 v170, v170, 0, s[56:57]
	v_cndmask_b32_e64 v171, v171, 0, s[58:59]
	v_cndmask_b32_e64 v172, v172, 0, s[44:45]
	v_cndmask_b32_e64 v173, v173, 0, s[46:47]
	v_cndmask_b32_e64 v174, v174, 0, s[60:61]
	v_cndmask_b32_e64 v175, v175, 0, s[62:63]
	v_cndmask_b32_e64 v176, v176, 0, s[48:49]
	v_cndmask_b32_e64 v177, v177, 0, s[50:51]
	v_cndmask_b32_e64 v178, v178, 0, s[64:65]
	v_cndmask_b32_e64 v179, v179, 0, s[66:67]
	s_mov_b64 s[2:3], 0
